# merge epilogue: gate (G) loads marked non-temporal so the read-once stream does not evict the M read-modify-write lines from L2
# speedup vs baseline: 1.0124x; 1.0025x over previous
.LBB0_670:
	s_add_i32 s44, s14, 2
	s_add_u32 s15, s8, 0xfffc0080
	s_addc_u32 s16, s9, -1
	s_add_i32 s45, 0, 0x10000
	v_add_u32_e32 v140, s45, v237
	ds_read_b128 v[128:131], v140
	ds_read_b128 v[132:135], v140 offset:1024
	ds_read_b128 v[136:139], v140 offset:2048
	ds_read_b128 v[140:143], v140 offset:3072
	s_cmp_eq_u32 s41, s14
	s_cselect_b32 s14, s12, s42
	s_cselect_b32 s17, s11, s16
	s_cselect_b32 s16, s10, s15
	s_cselect_b32 s15, s13, s43
	v_lshl_add_u64 v[176:177], s[8:9], 0, v[206:207]
	s_add_i32 m0, s24, 0xc000
	ds_read_b128 v[144:147], v242
	ds_read_b128 v[148:151], v242 offset:1024
	ds_read_b128 v[152:155], v242 offset:2048
	ds_read_b128 v[156:159], v242 offset:3072
	ds_read_b128 v[160:163], v242 offset:4096
	ds_read_b128 v[164:167], v242 offset:5120
	ds_read_b128 v[168:171], v242 offset:6144
	ds_read_b128 v[172:175], v242 offset:7168
	global_load_lds_dwordx4 v[176:177], off
	v_lshl_add_u64 v[176:177], s[8:9], 0, v[208:209]
	s_add_i32 m0, s24, 0xe000
	s_nop 0
	global_load_lds_dwordx4 v[176:177], off
	s_waitcnt lgkmcnt(8)
	s_barrier
	s_waitcnt lgkmcnt(0)
	s_setprio 1
	s_waitcnt lgkmcnt(0)
	v_mfma_f32_16x16x32_bf16 v[124:127], v[128:131], v[144:147], v[124:127]
	v_mfma_f32_16x16x32_bf16 v[120:123], v[136:139], v[144:147], v[120:123]
	v_mfma_f32_16x16x32_bf16 v[112:115], v[128:131], v[152:155], v[112:115]
	v_mfma_f32_16x16x32_bf16 v[104:107], v[136:139], v[152:155], v[104:107]
	v_mfma_f32_16x16x32_bf16 v[96:99], v[128:131], v[160:163], v[96:99]
	v_mfma_f32_16x16x32_bf16 v[88:91], v[136:139], v[160:163], v[88:91]
	v_mfma_f32_16x16x32_bf16 v[80:83], v[128:131], v[168:171], v[80:83]
	v_mfma_f32_16x16x32_bf16 v[72:75], v[136:139], v[168:171], v[72:75]
	v_mfma_f32_16x16x32_bf16 v[124:127], v[132:135], v[148:151], v[124:127]
	v_mfma_f32_16x16x32_bf16 v[120:123], v[140:143], v[148:151], v[120:123]
	v_mfma_f32_16x16x32_bf16 v[112:115], v[132:135], v[156:159], v[112:115]
	v_mfma_f32_16x16x32_bf16 v[104:107], v[140:143], v[156:159], v[104:107]
	v_mfma_f32_16x16x32_bf16 v[96:99], v[132:135], v[164:167], v[96:99]
	v_mfma_f32_16x16x32_bf16 v[88:91], v[140:143], v[164:167], v[88:91]
	v_mfma_f32_16x16x32_bf16 v[80:83], v[132:135], v[172:175], v[80:83]
	v_mfma_f32_16x16x32_bf16 v[72:75], v[140:143], v[172:175], v[72:75]
	s_setprio 0
	s_barrier
	s_add_i32 s48, 0, 0x14000
	s_add_i32 s45, s45, s23
	v_add_u32_e32 v188, s48, v237
	v_lshl_add_u64 v[192:193], s[14:15], 0, v[194:195]
	s_mov_b32 m0, s45
	ds_read_b128 v[176:179], v188
	ds_read_b128 v[180:183], v188 offset:1024
	ds_read_b128 v[184:187], v188 offset:2048
	ds_read_b128 v[188:191], v188 offset:3072
	global_load_lds_dwordx4 v[192:193], off
	v_lshl_add_u64 v[210:211], s[14:15], 0, v[204:205]
	s_add_i32 m0, s45, 0x2000
	s_nop 0
	global_load_lds_dwordx4 v[210:211], off
	s_barrier
	s_waitcnt lgkmcnt(0)
	s_setprio 1
	s_waitcnt lgkmcnt(0)
	v_mfma_f32_16x16x32_bf16 v[116:119], v[176:179], v[144:147], v[116:119]
	v_mfma_f32_16x16x32_bf16 v[108:111], v[184:187], v[144:147], v[108:111]
	v_mfma_f32_16x16x32_bf16 v[100:103], v[176:179], v[152:155], v[100:103]
	v_mfma_f32_16x16x32_bf16 v[92:95], v[184:187], v[152:155], v[92:95]
	v_mfma_f32_16x16x32_bf16 v[84:87], v[176:179], v[160:163], v[84:87]
	v_mfma_f32_16x16x32_bf16 v[76:79], v[184:187], v[160:163], v[76:79]
	v_mfma_f32_16x16x32_bf16 v[68:71], v[176:179], v[168:171], v[68:71]
	v_mfma_f32_16x16x32_bf16 v[64:67], v[184:187], v[168:171], v[64:67]
	v_mfma_f32_16x16x32_bf16 v[116:119], v[180:183], v[148:151], v[116:119]
	v_mfma_f32_16x16x32_bf16 v[108:111], v[188:191], v[148:151], v[108:111]
	v_mfma_f32_16x16x32_bf16 v[100:103], v[180:183], v[156:159], v[100:103]
	v_mfma_f32_16x16x32_bf16 v[92:95], v[188:191], v[156:159], v[92:95]
	v_mfma_f32_16x16x32_bf16 v[84:87], v[180:183], v[164:167], v[84:87]
	v_mfma_f32_16x16x32_bf16 v[76:79], v[188:191], v[164:167], v[76:79]
	v_mfma_f32_16x16x32_bf16 v[68:71], v[180:183], v[172:175], v[68:71]
	v_mfma_f32_16x16x32_bf16 v[64:67], v[188:191], v[172:175], v[64:67]
	s_setprio 0
	s_mov_b32 m0, s24
	v_lshl_add_u64 v[212:213], s[16:17], 0, v[194:195]
	s_barrier
	ds_read_b128 v[144:147], v242 offset:16384
	ds_read_b128 v[148:151], v242 offset:17408
	ds_read_b128 v[152:155], v242 offset:18432
	ds_read_b128 v[156:159], v242 offset:19456
	ds_read_b128 v[160:163], v242 offset:20480
	ds_read_b128 v[164:167], v242 offset:21504
	ds_read_b128 v[168:171], v242 offset:22528
	ds_read_b128 v[172:175], v242 offset:23552
	global_load_lds_dwordx4 v[212:213], off
	v_lshl_add_u64 v[214:215], s[16:17], 0, v[204:205]
	s_mov_b32 m0, s25
	s_nop 0
	global_load_lds_dwordx4 v[214:215], off
	s_barrier
	s_waitcnt lgkmcnt(0)
	s_setprio 1
	s_waitcnt lgkmcnt(0)
	v_mfma_f32_16x16x32_bf16 v[60:63], v[128:131], v[144:147], v[60:63]
	v_mfma_f32_16x16x32_bf16 v[56:59], v[136:139], v[144:147], v[56:59]
	v_mfma_f32_16x16x32_bf16 v[48:51], v[128:131], v[152:155], v[48:51]
	v_mfma_f32_16x16x32_bf16 v[40:43], v[136:139], v[152:155], v[40:43]
	v_mfma_f32_16x16x32_bf16 v[32:35], v[128:131], v[160:163], v[32:35]
	v_mfma_f32_16x16x32_bf16 v[24:27], v[136:139], v[160:163], v[24:27]
	v_mfma_f32_16x16x32_bf16 v[16:19], v[128:131], v[168:171], v[16:19]
	v_mfma_f32_16x16x32_bf16 v[8:11], v[136:139], v[168:171], v[8:11]
	v_mfma_f32_16x16x32_bf16 v[60:63], v[132:135], v[148:151], v[60:63]
	v_mfma_f32_16x16x32_bf16 v[56:59], v[140:143], v[148:151], v[56:59]
	v_mfma_f32_16x16x32_bf16 v[48:51], v[132:135], v[156:159], v[48:51]
	v_mfma_f32_16x16x32_bf16 v[40:43], v[140:143], v[156:159], v[40:43]
	v_mfma_f32_16x16x32_bf16 v[32:35], v[132:135], v[164:167], v[32:35]
	v_mfma_f32_16x16x32_bf16 v[24:27], v[140:143], v[164:167], v[24:27]
	v_mfma_f32_16x16x32_bf16 v[16:19], v[132:135], v[172:175], v[16:19]
	v_mfma_f32_16x16x32_bf16 v[8:11], v[140:143], v[172:175], v[8:11]
	s_setprio 0
	s_barrier
	s_add_u32 s46, s14, 0x40000
	s_addc_u32 s47, s15, 0
	s_add_i32 s45, s48, s23
	v_lshl_add_u64 v[128:129], s[46:47], 0, v[194:195]
	s_mov_b32 m0, s45
	s_nop 0
	global_load_lds_dwordx4 v[128:129], off
	v_lshl_add_u64 v[128:129], s[46:47], 0, v[204:205]
	s_add_i32 m0, s45, 0x2000
	s_nop 0
	global_load_lds_dwordx4 v[128:129], off
	s_waitcnt vmcnt(6)
	s_barrier
	s_setprio 1
	v_mfma_f32_16x16x32_bf16 v[52:55], v[176:179], v[144:147], v[52:55]
	v_mfma_f32_16x16x32_bf16 v[44:47], v[184:187], v[144:147], v[44:47]
	v_mfma_f32_16x16x32_bf16 v[36:39], v[176:179], v[152:155], v[36:39]
	v_mfma_f32_16x16x32_bf16 v[28:31], v[184:187], v[152:155], v[28:31]
	v_mfma_f32_16x16x32_bf16 v[20:23], v[176:179], v[160:163], v[20:23]
	v_mfma_f32_16x16x32_bf16 v[12:15], v[184:187], v[160:163], v[12:15]
	v_mfma_f32_16x16x32_bf16 v[4:7], v[176:179], v[168:171], v[4:7]
	v_mfma_f32_16x16x32_bf16 v[0:3], v[184:187], v[168:171], v[0:3]
	v_mfma_f32_16x16x32_bf16 v[52:55], v[180:183], v[148:151], v[52:55]
	v_mfma_f32_16x16x32_bf16 v[44:47], v[188:191], v[148:151], v[44:47]
	v_mfma_f32_16x16x32_bf16 v[36:39], v[180:183], v[156:159], v[36:39]
	v_mfma_f32_16x16x32_bf16 v[28:31], v[188:191], v[156:159], v[28:31]
	v_mfma_f32_16x16x32_bf16 v[20:23], v[180:183], v[164:167], v[20:23]
	v_mfma_f32_16x16x32_bf16 v[12:15], v[188:191], v[164:167], v[12:15]
	v_mfma_f32_16x16x32_bf16 v[4:7], v[180:183], v[172:175], v[4:7]
	v_mfma_f32_16x16x32_bf16 v[0:3], v[188:191], v[172:175], v[0:3]
	s_setprio 0
	s_add_i32 s45, 0, 0x18000
	v_add_u32_e32 v140, s45, v237
	s_barrier
	ds_read_b128 v[128:131], v140
	ds_read_b128 v[132:135], v140 offset:1024
	ds_read_b128 v[136:139], v140 offset:2048
	ds_read_b128 v[140:143], v140 offset:3072
	s_add_u32 s16, s16, 0x40000
	s_addc_u32 s17, s17, 0
	s_mov_b32 m0, s26
	v_lshl_add_u64 v[176:177], s[16:17], 0, v[194:195]
	ds_read_b128 v[144:147], v242 offset:32768
	ds_read_b128 v[148:151], v242 offset:33792
	ds_read_b128 v[152:155], v242 offset:34816
	ds_read_b128 v[156:159], v242 offset:35840
	ds_read_b128 v[160:163], v242 offset:36864
	ds_read_b128 v[164:167], v242 offset:37888
	ds_read_b128 v[168:171], v242 offset:38912
	ds_read_b128 v[172:175], v242 offset:39936
	global_load_lds_dwordx4 v[176:177], off
	v_lshl_add_u64 v[176:177], s[16:17], 0, v[204:205]
	s_mov_b32 m0, s27
	s_nop 0
	global_load_lds_dwordx4 v[176:177], off
	s_waitcnt lgkmcnt(8)
	s_barrier
	s_waitcnt lgkmcnt(0)
	s_setprio 1
	s_waitcnt lgkmcnt(0)
	v_mfma_f32_16x16x32_bf16 v[124:127], v[128:131], v[144:147], v[124:127]
	v_mfma_f32_16x16x32_bf16 v[120:123], v[136:139], v[144:147], v[120:123]
	v_mfma_f32_16x16x32_bf16 v[112:115], v[128:131], v[152:155], v[112:115]
	v_mfma_f32_16x16x32_bf16 v[104:107], v[136:139], v[152:155], v[104:107]
	v_mfma_f32_16x16x32_bf16 v[96:99], v[128:131], v[160:163], v[96:99]
	v_mfma_f32_16x16x32_bf16 v[88:91], v[136:139], v[160:163], v[88:91]
	v_mfma_f32_16x16x32_bf16 v[80:83], v[128:131], v[168:171], v[80:83]
	v_mfma_f32_16x16x32_bf16 v[72:75], v[136:139], v[168:171], v[72:75]
	v_mfma_f32_16x16x32_bf16 v[124:127], v[132:135], v[148:151], v[124:127]
	v_mfma_f32_16x16x32_bf16 v[120:123], v[140:143], v[148:151], v[120:123]
	v_mfma_f32_16x16x32_bf16 v[112:115], v[132:135], v[156:159], v[112:115]
	v_mfma_f32_16x16x32_bf16 v[104:107], v[140:143], v[156:159], v[104:107]
	v_mfma_f32_16x16x32_bf16 v[96:99], v[132:135], v[164:167], v[96:99]
	v_mfma_f32_16x16x32_bf16 v[88:91], v[140:143], v[164:167], v[88:91]
	v_mfma_f32_16x16x32_bf16 v[80:83], v[132:135], v[172:175], v[80:83]
	v_mfma_f32_16x16x32_bf16 v[72:75], v[140:143], v[172:175], v[72:75]
	s_setprio 0
	s_barrier
	s_add_i32 s16, 0, 0x1c000
	s_add_i32 s17, s45, s23
	v_add_u32_e32 v188, s16, v237
	v_lshl_add_u64 v[192:193], v[192:193], 0, s[82:83]
	s_mov_b32 m0, s17
	ds_read_b128 v[176:179], v188
	ds_read_b128 v[180:183], v188 offset:1024
	ds_read_b128 v[184:187], v188 offset:2048
	ds_read_b128 v[188:191], v188 offset:3072
	global_load_lds_dwordx4 v[192:193], off
	v_lshl_add_u64 v[192:193], v[210:211], 0, s[82:83]
	s_add_i32 m0, s17, 0x2000
	s_nop 0
	global_load_lds_dwordx4 v[192:193], off
	s_barrier
	s_waitcnt lgkmcnt(0)
	s_setprio 1
	s_waitcnt lgkmcnt(0)
	v_mfma_f32_16x16x32_bf16 v[116:119], v[176:179], v[144:147], v[116:119]
	v_mfma_f32_16x16x32_bf16 v[108:111], v[184:187], v[144:147], v[108:111]
	v_mfma_f32_16x16x32_bf16 v[100:103], v[176:179], v[152:155], v[100:103]
	v_mfma_f32_16x16x32_bf16 v[92:95], v[184:187], v[152:155], v[92:95]
	v_mfma_f32_16x16x32_bf16 v[84:87], v[176:179], v[160:163], v[84:87]
	v_mfma_f32_16x16x32_bf16 v[76:79], v[184:187], v[160:163], v[76:79]
	v_mfma_f32_16x16x32_bf16 v[68:71], v[176:179], v[168:171], v[68:71]
	v_mfma_f32_16x16x32_bf16 v[64:67], v[184:187], v[168:171], v[64:67]
	v_mfma_f32_16x16x32_bf16 v[116:119], v[180:183], v[148:151], v[116:119]
	v_mfma_f32_16x16x32_bf16 v[108:111], v[188:191], v[148:151], v[108:111]
	v_mfma_f32_16x16x32_bf16 v[100:103], v[180:183], v[156:159], v[100:103]
	v_mfma_f32_16x16x32_bf16 v[92:95], v[188:191], v[156:159], v[92:95]
	v_mfma_f32_16x16x32_bf16 v[84:87], v[180:183], v[164:167], v[84:87]
	v_mfma_f32_16x16x32_bf16 v[76:79], v[188:191], v[164:167], v[76:79]
	v_mfma_f32_16x16x32_bf16 v[68:71], v[180:183], v[172:175], v[68:71]
	v_mfma_f32_16x16x32_bf16 v[64:67], v[188:191], v[172:175], v[64:67]
	s_setprio 0
	s_mov_b32 m0, s28
	v_lshl_add_u64 v[192:193], v[212:213], 0, s[82:83]
	s_barrier
	ds_read_b128 v[144:147], v242 offset:49152
	ds_read_b128 v[148:151], v242 offset:50176
	ds_read_b128 v[152:155], v242 offset:51200
	ds_read_b128 v[156:159], v242 offset:52224
	ds_read_b128 v[160:163], v242 offset:53248
	ds_read_b128 v[164:167], v242 offset:54272
	ds_read_b128 v[168:171], v242 offset:55296
	ds_read_b128 v[172:175], v242 offset:56320
	global_load_lds_dwordx4 v[192:193], off
	v_lshl_add_u64 v[192:193], v[214:215], 0, s[82:83]
	s_mov_b32 m0, s29
	s_nop 0
	global_load_lds_dwordx4 v[192:193], off
	s_barrier
	s_waitcnt lgkmcnt(0)
	s_setprio 1
	s_waitcnt lgkmcnt(0)
	v_mfma_f32_16x16x32_bf16 v[60:63], v[128:131], v[144:147], v[60:63]
	v_mfma_f32_16x16x32_bf16 v[56:59], v[136:139], v[144:147], v[56:59]
	v_mfma_f32_16x16x32_bf16 v[48:51], v[128:131], v[152:155], v[48:51]
	v_mfma_f32_16x16x32_bf16 v[40:43], v[136:139], v[152:155], v[40:43]
	v_mfma_f32_16x16x32_bf16 v[32:35], v[128:131], v[160:163], v[32:35]
	v_mfma_f32_16x16x32_bf16 v[24:27], v[136:139], v[160:163], v[24:27]
	v_mfma_f32_16x16x32_bf16 v[16:19], v[128:131], v[168:171], v[16:19]
	v_mfma_f32_16x16x32_bf16 v[8:11], v[136:139], v[168:171], v[8:11]
	v_mfma_f32_16x16x32_bf16 v[60:63], v[132:135], v[148:151], v[60:63]
	v_mfma_f32_16x16x32_bf16 v[56:59], v[140:143], v[148:151], v[56:59]
	v_mfma_f32_16x16x32_bf16 v[48:51], v[132:135], v[156:159], v[48:51]
	v_mfma_f32_16x16x32_bf16 v[40:43], v[140:143], v[156:159], v[40:43]
	v_mfma_f32_16x16x32_bf16 v[32:35], v[132:135], v[164:167], v[32:35]
	v_mfma_f32_16x16x32_bf16 v[24:27], v[140:143], v[164:167], v[24:27]
	v_mfma_f32_16x16x32_bf16 v[16:19], v[132:135], v[172:175], v[16:19]
	v_mfma_f32_16x16x32_bf16 v[8:11], v[140:143], v[172:175], v[8:11]
	s_setprio 0
	s_barrier
	s_add_u32 s14, s14, 0x40080
	s_addc_u32 s15, s15, 0
	s_add_i32 s16, s16, s23
	v_lshl_add_u64 v[128:129], s[14:15], 0, v[194:195]
	s_mov_b32 m0, s16
	s_nop 0
	global_load_lds_dwordx4 v[128:129], off
	v_lshl_add_u64 v[128:129], s[14:15], 0, v[204:205]
	s_add_i32 m0, s16, 0x2000
	s_nop 0
	global_load_lds_dwordx4 v[128:129], off
	s_waitcnt vmcnt(6)
	s_barrier
	s_setprio 1
	v_mfma_f32_16x16x32_bf16 v[52:55], v[176:179], v[144:147], v[52:55]
	v_mfma_f32_16x16x32_bf16 v[44:47], v[184:187], v[144:147], v[44:47]
	v_mfma_f32_16x16x32_bf16 v[36:39], v[176:179], v[152:155], v[36:39]
	v_mfma_f32_16x16x32_bf16 v[28:31], v[184:187], v[152:155], v[28:31]
	v_mfma_f32_16x16x32_bf16 v[20:23], v[176:179], v[160:163], v[20:23]
	v_mfma_f32_16x16x32_bf16 v[12:15], v[184:187], v[160:163], v[12:15]
	v_mfma_f32_16x16x32_bf16 v[4:7], v[176:179], v[168:171], v[4:7]
	v_mfma_f32_16x16x32_bf16 v[0:3], v[184:187], v[168:171], v[0:3]
	v_mfma_f32_16x16x32_bf16 v[52:55], v[180:183], v[148:151], v[52:55]
	v_mfma_f32_16x16x32_bf16 v[44:47], v[188:191], v[148:151], v[44:47]
	v_mfma_f32_16x16x32_bf16 v[36:39], v[180:183], v[156:159], v[36:39]
	v_mfma_f32_16x16x32_bf16 v[28:31], v[188:191], v[156:159], v[28:31]
	v_mfma_f32_16x16x32_bf16 v[20:23], v[180:183], v[164:167], v[20:23]
	v_mfma_f32_16x16x32_bf16 v[12:15], v[188:191], v[164:167], v[12:15]
	v_mfma_f32_16x16x32_bf16 v[4:7], v[180:183], v[172:175], v[4:7]
	v_mfma_f32_16x16x32_bf16 v[0:3], v[188:191], v[172:175], v[0:3]
	s_setprio 0
	s_add_u32 s8, s8, 0x100
	s_addc_u32 s9, s9, 0
	s_add_u32 s42, s42, 0x100
	s_addc_u32 s43, s43, 0
	s_cmp_ge_i32 s44, s40
	s_mov_b32 s14, s44
	s_barrier
	s_cbranch_scc0 .LBB0_670
	s_lshl_b32 s8, s37, 10
	s_ashr_i32 s9, s8, 31
	s_cmp_gt_i32 s37, 0
	s_cselect_b64 s[16:17], -1, 0
	s_lshl_b32 s39, s39, 8
	s_lshl_b64 s[8:9], s[8:9], 1
	s_add_u32 s14, s3, s8
	s_addc_u32 s15, s18, s9
	v_add_u32_e32 v210, s39, v236
	v_lshl_or_b32 v212, s38, 8, v241
	v_mov_b64_e32 v[128:129], s[14:15]
	v_mad_i64_i32 v[128:129], s[8:9], v210, s81, v[128:129]
	v_ashrrev_i32_e32 v213, 31, v212
	v_lshl_add_u64 v[130:131], v[212:213], 1, v[128:129]
	global_load_dwordx4 v[186:189], v[130:131], off nt
	v_ashrrev_i32_e32 v211, 31, v210
	v_lshlrev_b64 v[128:129], 11, v[210:211]
	v_lshl_add_u64 v[214:215], s[0:1], 0, v[128:129]
	s_cmp_lt_i32 s37, 1
	v_lshl_add_u64 v[128:129], v[212:213], 1, v[214:215]
	s_cbranch_scc1 .LBB0_673
	v_mov_b32_e32 v190, v243
	v_mov_b32_e32 v191, v244
	v_mov_b32_e32 v192, v245
	v_mov_b32_e32 v193, v246
	s_branch .LBB0_674

.LBB0_674:
	global_load_dwordx4 v[178:181], v[130:131], off offset:256 nt
	v_cndmask_b32_e64 v130, 0, 1, s[16:17]
	v_mov_b32_e32 v158, 0
	v_cmp_ne_u32_e64 s[8:9], 1, v130
	s_andn2_b64 vcc, exec, s[16:17]
	v_mov_b32_e32 v182, 0
	v_mov_b32_e32 v183, 0
	v_mov_b32_e32 v184, 0
	v_mov_b32_e32 v185, 0
	s_cbranch_vccnz .LBB0_676
	v_mov_b32_e32 v182, v247
	v_mov_b32_e32 v183, v248
	v_mov_b32_e32 v184, v249
	v_mov_b32_e32 v185, v250
.LBB0_676:
	v_or_b32_e32 v128, 16, v210
	v_mov_b64_e32 v[130:131], s[14:15]
	v_mad_i64_i32 v[130:131], s[16:17], v128, s81, v[130:131]
	v_lshl_add_u64 v[130:131], v[212:213], 1, v[130:131]
	global_load_dwordx4 v[174:177], v[130:131], off nt
	v_ashrrev_i32_e32 v129, 31, v128
	v_lshlrev_b64 v[128:129], 11, v[128:129]
	v_lshl_add_u64 v[128:129], s[0:1], 0, v[128:129]
	s_and_b64 vcc, exec, s[8:9]
	v_lshl_add_u64 v[128:129], v[212:213], 1, v[128:129]
	v_mov_b32_e32 v159, 0
	v_mov_b32_e32 v160, 0
	v_mov_b32_e32 v161, 0
	s_cbranch_vccnz .LBB0_678
	v_mov_b32_e32 v158, v251
	v_mov_b32_e32 v159, v255
	v_mov_b32_e32 v160, v196
	v_mov_b32_e32 v161, v198
.LBB0_678:
	global_load_dwordx4 v[166:169], v[130:131], off offset:256 nt
	v_mov_b32_e32 v146, 0
	s_and_b64 vcc, exec, s[8:9]
	v_mov_b32_e32 v170, 0
	v_mov_b32_e32 v171, 0
	v_mov_b32_e32 v172, 0
	v_mov_b32_e32 v173, 0
	s_cbranch_vccnz .LBB0_680
	v_mov_b32_e32 v170, v199
	v_mov_b32_e32 v171, v200
	v_mov_b32_e32 v172, v201
	v_mov_b32_e32 v173, v218
.LBB0_680:
	v_or_b32_e32 v128, 32, v210
	v_mov_b64_e32 v[130:131], s[14:15]
	v_mad_i64_i32 v[130:131], s[16:17], v128, s81, v[130:131]
	v_lshl_add_u64 v[130:131], v[212:213], 1, v[130:131]
	global_load_dwordx4 v[162:165], v[130:131], off nt
	v_ashrrev_i32_e32 v129, 31, v128
	v_lshlrev_b64 v[128:129], 11, v[128:129]
	v_lshl_add_u64 v[128:129], s[0:1], 0, v[128:129]
	s_and_b64 vcc, exec, s[8:9]
	v_lshl_add_u64 v[128:129], v[212:213], 1, v[128:129]
	v_mov_b32_e32 v147, 0
	v_mov_b32_e32 v148, 0
	v_mov_b32_e32 v149, 0
	s_cbranch_vccnz .LBB0_682
	v_mov_b32_e32 v146, v219
	v_mov_b32_e32 v147, v220
	v_mov_b32_e32 v148, v222
	v_mov_b32_e32 v149, v223
.LBB0_682:
	global_load_dwordx4 v[150:153], v[130:131], off offset:256 nt
	v_mov_b32_e32 v130, 0
	s_and_b64 vcc, exec, s[8:9]
	v_mov_b32_e32 v154, 0
	v_mov_b32_e32 v155, 0
	v_mov_b32_e32 v156, 0
	v_mov_b32_e32 v157, 0
	s_cbranch_vccnz .LBB0_684
	v_mov_b32_e32 v154, v224
	v_mov_b32_e32 v155, v225
	v_mov_b32_e32 v156, v226
	v_mov_b32_e32 v157, v227
.LBB0_684:
	v_or_b32_e32 v132, 48, v210
	v_mov_b64_e32 v[128:129], s[14:15]
	v_mad_i64_i32 v[128:129], s[16:17], v132, s81, v[128:129]
	v_lshl_add_u64 v[128:129], v[212:213], 1, v[128:129]
	global_load_dwordx4 v[142:145], v[128:129], off nt
	v_ashrrev_i32_e32 v133, 31, v132
	v_lshlrev_b64 v[132:133], 11, v[132:133]
	v_lshl_add_u64 v[132:133], s[0:1], 0, v[132:133]
	s_and_b64 vcc, exec, s[8:9]
	v_lshl_add_u64 v[216:217], v[212:213], 1, v[132:133]
	v_mov_b32_e32 v131, 0
	v_mov_b32_e32 v132, 0
	v_mov_b32_e32 v133, 0
	s_cbranch_vccnz .LBB0_686
	v_mov_b32_e32 v130, v228
	v_mov_b32_e32 v131, v229
	v_mov_b32_e32 v132, v230
	v_mov_b32_e32 v133, v231
.LBB0_686:
	global_load_dwordx4 v[134:137], v[128:129], off offset:256 nt
	v_mov_b32_e32 v128, 0
	s_and_b64 vcc, exec, s[8:9]
	v_mov_b32_e32 v138, 0
	v_mov_b32_e32 v139, 0
	v_mov_b32_e32 v140, 0
	v_mov_b32_e32 v141, 0
	s_cbranch_vccnz .LBB0_688
	v_mov_b32_e32 v138, v232
	v_mov_b32_e32 v139, v233
	v_mov_b32_e32 v140, v234
	v_mov_b32_e32 v141, v235

.Lmrs_6:
	v_cvt_pk_bf16_f32 v72, v72, v68
	v_lshlrev_b32_e32 v68, 16, v139
	v_lshlrev_b32_e32 v69, 16, v135
	v_fmac_f32_e32 v68, v70, v69
	v_and_b32_e32 v69, 0xffff0000, v139
	v_and_b32_e32 v70, 0xffff0000, v135
	v_fmac_f32_e32 v69, v71, v70
	v_cvt_pk_bf16_f32 v73, v68, v69
	v_lshlrev_b32_e32 v68, 16, v140
	v_lshlrev_b32_e32 v69, 16, v136
	v_fmac_f32_e32 v68, v64, v69
	v_and_b32_e32 v64, 0xffff0000, v140
	v_and_b32_e32 v69, 0xffff0000, v136
	v_fmac_f32_e32 v64, v65, v69
	v_cvt_pk_bf16_f32 v74, v68, v64
	v_lshlrev_b32_e32 v64, 16, v141
	v_lshlrev_b32_e32 v65, 16, v137
	v_fmac_f32_e32 v64, v66, v65
	v_and_b32_e32 v65, 0xffff0000, v141
	v_and_b32_e32 v66, 0xffff0000, v137
	v_fmac_f32_e32 v65, v67, v66
	v_cvt_pk_bf16_f32 v75, v64, v65
	v_add_u32_e32 v66, 0x80, v210
	v_mov_b64_e32 v[64:65], s[14:15]
	v_mad_i64_i32 v[64:65], s[16:17], v66, s81, v[64:65]
	v_lshl_add_u64 v[68:69], v[64:65], 0, v[124:125]
	global_load_dwordx4 v[120:123], v[68:69], off nt
	v_ashrrev_i32_e32 v67, 31, v66
	v_lshlrev_b64 v[64:65], 11, v[66:67]
	v_lshl_add_u64 v[126:127], s[0:1], 0, v[64:65]
	s_and_b64 vcc, exec, s[8:9]
	v_lshl_add_u64 v[64:65], v[212:213], 1, v[126:127]
	v_mov_b32_e32 v129, 0
	v_mov_b32_e32 v130, 0
	v_mov_b32_e32 v131, 0
	v_mov_b32_e32 v232, v72
	v_mov_b32_e32 v233, v73
	v_mov_b32_e32 v234, v74
	v_mov_b32_e32 v235, v75
	s_cmp_lg_u32 s37, 2
	s_cbranch_scc1 .Lmrs_7
	global_store_dwordx4 v[80:81], v[72:75], off offset:256

.LBB0_690:
	global_load_dwordx4 v[112:115], v[68:69], off offset:256 nt
	v_mov_b32_e32 v96, 0
	s_and_b64 vcc, exec, s[8:9]
	v_mov_b32_e32 v116, 0
	v_mov_b32_e32 v117, 0
	v_mov_b32_e32 v118, 0
	v_mov_b32_e32 v119, 0
	s_cbranch_vccnz .LBB0_692
	global_load_dwordx4 v[116:119], v[64:65], off offset:256
.LBB0_692:
	v_or_b32_e32 v64, 16, v66
	v_mov_b64_e32 v[68:69], s[14:15]
	v_mad_i64_i32 v[68:69], s[16:17], v64, s81, v[68:69]
	v_lshl_add_u64 v[68:69], v[212:213], 1, v[68:69]
	global_load_dwordx4 v[108:111], v[68:69], off nt
	v_ashrrev_i32_e32 v65, 31, v64
	v_lshlrev_b64 v[64:65], 11, v[64:65]
	v_lshl_add_u64 v[64:65], s[0:1], 0, v[64:65]
	s_and_b64 vcc, exec, s[8:9]
	v_lshl_add_u64 v[64:65], v[212:213], 1, v[64:65]
	v_mov_b32_e32 v97, 0
	v_mov_b32_e32 v98, 0
	v_mov_b32_e32 v99, 0
	s_cbranch_vccnz .LBB0_694
	global_load_dwordx4 v[96:99], v[64:65], off
.LBB0_694:
	global_load_dwordx4 v[100:103], v[68:69], off offset:256 nt
	v_mov_b32_e32 v80, 0
	s_and_b64 vcc, exec, s[8:9]
	v_mov_b32_e32 v104, 0
	v_mov_b32_e32 v105, 0
	v_mov_b32_e32 v106, 0
	v_mov_b32_e32 v107, 0
	s_cbranch_vccnz .LBB0_696
	global_load_dwordx4 v[104:107], v[64:65], off offset:256
.LBB0_696:
	v_or_b32_e32 v68, 32, v66
	v_mov_b64_e32 v[64:65], s[14:15]
	v_mad_i64_i32 v[64:65], s[16:17], v68, s81, v[64:65]
	v_lshl_add_u64 v[64:65], v[212:213], 1, v[64:65]
	global_load_dwordx4 v[92:95], v[64:65], off nt
	v_ashrrev_i32_e32 v69, 31, v68
	v_lshlrev_b64 v[68:69], 11, v[68:69]
	v_lshl_add_u64 v[68:69], s[0:1], 0, v[68:69]
	s_and_b64 vcc, exec, s[8:9]
	v_lshl_add_u64 v[68:69], v[212:213], 1, v[68:69]
	v_mov_b32_e32 v81, 0
	v_mov_b32_e32 v82, 0
	v_mov_b32_e32 v83, 0
	s_cbranch_vccnz .LBB0_698
	global_load_dwordx4 v[80:83], v[68:69], off
.LBB0_698:
	global_load_dwordx4 v[84:87], v[64:65], off offset:256 nt
	v_mov_b32_e32 v64, 0
	s_and_b64 vcc, exec, s[8:9]
	v_mov_b32_e32 v88, 0
	v_mov_b32_e32 v89, 0
	v_mov_b32_e32 v90, 0
	v_mov_b32_e32 v91, 0
	s_cbranch_vccnz .LBB0_700
	global_load_dwordx4 v[88:91], v[68:69], off offset:256
.LBB0_700:
	v_or_b32_e32 v66, 48, v66
	v_mov_b64_e32 v[68:69], s[14:15]
	v_mad_i64_i32 v[68:69], s[14:15], v66, s81, v[68:69]
	v_lshl_add_u64 v[68:69], v[212:213], 1, v[68:69]
	global_load_dwordx4 v[76:79], v[68:69], off nt
	v_ashrrev_i32_e32 v67, 31, v66
	v_lshlrev_b64 v[66:67], 11, v[66:67]
	v_lshl_add_u64 v[66:67], s[0:1], 0, v[66:67]
	s_and_b64 vcc, exec, s[8:9]
	v_lshl_add_u64 v[72:73], v[212:213], 1, v[66:67]
	v_mov_b32_e32 v65, 0
	v_mov_b32_e32 v66, 0
	v_mov_b32_e32 v67, 0
	s_cbranch_vccnz .LBB0_702
	global_load_dwordx4 v[64:67], v[72:73], off
.LBB0_702:
	s_nop 0
	global_load_dwordx4 v[68:71], v[68:69], off offset:256 nt
	s_and_b64 vcc, exec, s[8:9]
	s_cbranch_vccz .LBB0_665
	v_mov_b32_e32 v72, 0
	v_mov_b32_e32 v73, 0
	v_mov_b32_e32 v74, 0
	v_mov_b32_e32 v75, 0
	s_branch .LBB0_666
